# next work item index requested from the epilogue (atomic round trip and store drain no longer exposed at each item start), both mixers
# baseline (speedup 1.0000x reference)
; #define LAS __attribute__((address_space(3)))
; __global__ void __launch_bounds__(NTHREADS) hybrid_fwd(Params p) {
;     extern __shared__ __attribute__((aligned(16))) unsigned char lds_raw[];
;     LAS unsigned char* lds = (LAS unsigned char*)lds_raw;
;     cg::grid_group grid = cg::this_grid();
;     bf16_t* hb = (bf16_t*)(p.ws + WS_HB);
;     bf16_t* z = (bf16_t*)(p.ws + WS_Z);
;     unsigned* barw = (unsigned*)(p.ws + WS_BAR);
;     volatile LAS unsigned* bst = (volatile LAS unsigned*)(lds + LDS_MAIN);
;     {
;         const int tid = threadIdx.x, lane = tid & 63, wave = __builtin_amdgcn_readfirstlane(tid >> 6);
;         const int G = gridDim.x, gw = blockIdx.x * NWAVES + wave, NGW = G * NWAVES;
;         if (tid < 2) bst[tid] = 0u;
;         if (blockIdx.x == 0) { for (int i = tid; i < XCD_BAR_WORDS; i += NTHREADS) barw[i] = 0u; for (int i = tid; i < 4 * 8 * 64; i += NTHREADS) ((unsigned*)(p.ws + WS_Q))[i] = 0u; }
_Z10hybrid_fwd6Params:
	s_mov_b32 s100, 0
	s_load_dwordx8 s[88:95], s[0:1], 0x40
	s_load_dword s99, s[0:1], 0x68
	s_add_u32 s6, s0, 0x68
	v_and_b32_e32 v34, 0x3ff, v0
	s_addc_u32 s7, s1, 0
	v_readfirstlane_b32 s16, v34
	v_cmp_gt_u32_e32 vcc, 2, v34
	s_and_saveexec_b64 s[8:9], vcc
	v_lshl_add_u32 v1, v34, 2, 0
	v_add_u32_e32 v1, 0x24000, v1
	v_mov_b32_e32 v2, 0
	ds_write_b32 v1, v2
	s_or_b64 exec, exec, s[8:9]
	s_waitcnt lgkmcnt(0)
	s_add_u32 s96, s94, 0x1c900000
	s_addc_u32 s97, s95, 0
	s_cmp_lg_u32 s2, 0
	s_mov_b32 s8, 0
	s_cbranch_scc1 .LBB0_14
	v_sub_u32_e32 v1, 0xd7f, v34
	v_lshrrev_b32_e32 v4, 9, v1
	v_add_u32_e32 v1, 2, v4
	v_add_u32_e32 v3, 0x200, v34
	v_mov_b32_e32 v2, v34
	v_and_b32_e32 v10, 14, v1
	v_mov_b32_e32 v5, v4
	v_mov_b32_e32 v1, v34
	s_mov_b64 s[10:11], 0
	s_mov_b32 s9, 1
	v_mov_b32_e32 v7, 0
	s_mov_b32 s12, s8
	v_mov_b64_e32 v[8:9], v[2:3]
	s_branch .LBB0_5

; DI bool attn_next(AttnQueue& q, int lane0, int& qs, int& hd) {
;     for (;;) {
;         if (q.cur >= 8) return false;
;         const int xq = (q.x + q.cur) & 7;
;         const int nqs = NQS / 8 + (xq == 7 ? 1 : 0);
;         unsigned n = 0;
;         if (lane0) n = __hip_atomic_fetch_add(q.heads + 64 * xq, 1u, __ATOMIC_RELAXED, __HIP_MEMORY_SCOPE_AGENT);
;         n = (unsigned)__builtin_amdgcn_readfirstlane((int)n);
;         if (n < (unsigned)(nqs * 16)) { qs = (NQS / 8) * xq + (int)(n >> 4); hd = (int)(n & 15u); return true; }
.LBB0_134:
	s_cmp_gt_i32 s26, 7
	s_cbranch_scc1 .LBB0_143
	s_add_i32 s0, s26, s33
	s_and_b32 s8, s0, 7
	s_cmp_eq_u32 s100, 0
	s_cbranch_scc1 .Lpref_none_139
	s_mov_b32 s100, 0
	s_waitcnt vmcnt(16)
	v_mov_b32_e32 v0, v240
	s_branch .Lpref_have_139
.Lpref_none_139:
	v_mov_b32_e32 v0, 0
	s_and_saveexec_b64 s[0:1], s[36:37]
	s_cbranch_execz .LBB0_139
	s_mov_b64 s[6:7], exec
	v_mbcnt_lo_u32_b32 v0, s6, 0
	v_mbcnt_hi_u32_b32 v0, s7, v0
	v_cmp_eq_u32_e32 vcc, 0, v0
	s_and_saveexec_b64 s[4:5], vcc
	s_cbranch_execz .LBB0_138
	s_lshl_b32 s9, s8, 8
	s_bcnt1_i32_b64 s6, s[6:7]
	v_mov_b32_e32 v2, s9
	v_mov_b32_e32 v3, s6
	global_atomic_add v2, v2, v3, s[34:35] sc0

; DI bool attn_next(AttnQueue& q, int lane0, int& qs, int& hd) {
;     for (;;) {
;         if (q.cur >= 8) return false;
;         const int xq = (q.x + q.cur) & 7;
;         const int nqs = NQS / 8 + (xq == 7 ? 1 : 0);
;         unsigned n = 0;
;         if (lane0) n = __hip_atomic_fetch_add(q.heads + 64 * xq, 1u, __ATOMIC_RELAXED, __HIP_MEMORY_SCOPE_AGENT);
;         n = (unsigned)__builtin_amdgcn_readfirstlane((int)n);
;         if (n < (unsigned)(nqs * 16)) { qs = (NQS / 8) * xq + (int)(n >> 4); hd = (int)(n & 15u); return true; }
.Lpref_have_139:
	s_cmp_eq_u32 s8, 7
	v_readfirstlane_b32 s6, v0
	s_cselect_b32 s4, s14, 0x400
	s_cmp_lt_u32 s6, s4
	s_cselect_b64 s[0:1], -1, 0
	s_cmp_ge_u32 s6, s4
	s_mov_b64 s[4:5], -1
	s_cbranch_scc0 .LBB0_141
	s_add_i32 s7, s26, 1
	s_mov_b64 s[4:5], 0

; DI unsigned pk2(float a, float b) { f32x2 v = {a, b}; bf16v2 r = __builtin_convertvector(v, bf16v2); return __builtin_bit_cast(unsigned, r); }
; DI float bf_lo(unsigned u) { return __uint_as_float(u << 16); }
; DI float bf_hi(unsigned u) { return __uint_as_float(u & 0xffff0000u); }
; DI size_t zrowU(int row0, int NT) { return ((size_t)((row0 >> 8) * NT) << 16) + (size_t)((((row0 >> 7) & 1) << 15) | (((row0 >> 5) & 1) << 14) | (((row0 >> 6) & 1) << 11)); }
; DI unsigned zlaneRC(int r5, int col) { return (unsigned)(((col >> 8) << 16) | ((r5 >> 4) << 13) | (((col >> 7) & 1) << 12) | (((col >> 5) & 3) << 9) | (((col >> 3) & 3) << 7) | ((r5 & 15) << 3) | (col & 7)); }
; DI float silu_mul(float o, float g) { return o * g * __builtin_amdgcn_rcpf(1.0f + __builtin_amdgcn_exp2f(g * -1.4426950408889634f)); }
; DI void attnB_item(bf16_t* z, int hh, int qs, LAS bf16_t* vs, int lane) {
;     ...
;     if (!metaq || c < NMETA) {
;         bf16_t* orow = z + zrowU(qrow0, 32) + zlaneRC(c, hh * 128 + 4 * h);
;         const bf16_t* grow = z + zrowU(qrow0, 32) + zlaneRC(c, 6144 + hh * 128 + 4 * h);
; #pragma unroll
;         for (int dt = 0; dt < 4; ++dt)
; #pragma unroll
;             for (int g = 0; g < 4; ++g) {
;                 const int d0 = (dt << 9) | (g << 7);
;                 const u32x2 gv = *(const u32x2*)(grow + d0);
;                 u32x2 o; o.x = pk2(silu_mul(acc[dt][4 * g], bf_lo(gv.x)), silu_mul(acc[dt][4 * g + 1], bf_hi(gv.x)));
;                 o.y = pk2(silu_mul(acc[dt][4 * g + 2], bf_lo(gv.y)), silu_mul(acc[dt][4 * g + 3], bf_hi(gv.y)));
;                 *(u32x2*)(orow + d0) = o;
;             }
;     }
; DI bool attn_next(AttnQueue& q, int lane0, int& qs, int& hd) {
;     for (;;) {
;         if (q.cur >= 8) return false;
;         const int xq = (q.x + q.cur) & 7;
;         const int nqs = NQS / 8 + (xq == 7 ? 1 : 0);
;         unsigned n = 0;
;         if (lane0) n = __hip_atomic_fetch_add(q.heads + 64 * xq, 1u, __ATOMIC_RELAXED, __HIP_MEMORY_SCOPE_AGENT);
;         n = (unsigned)__builtin_amdgcn_readfirstlane((int)n);
;         if (n < (unsigned)(nqs * 16)) { qs = (NQS / 8) * xq + (int)(n >> 4); hd = (int)(n & 15u); return true; }
.LBB0_157:
	v_cmp_gt_u32_e32 vcc, 16, v178
	s_or_b64 s[0:1], s[0:1], vcc
	s_and_saveexec_b64 s[4:5], s[0:1]
	s_xor_b64 s[0:1], exec, s[4:5]
	s_cbranch_execz .LBB0_130
	v_add_u32_e32 v0, s27, v183
	v_lshlrev_b32_e32 v66, 8, v0
	v_lshlrev_b32_e32 v0, 5, v0
	v_lshlrev_b32_e32 v67, 6, v180
	v_and_b32_e32 v0, 0x1000, v0
	v_and_b32_e32 v68, 0x780, v67
	v_and_b32_e32 v69, 4, v183
	v_or_b32_e32 v67, v68, v69
	v_and_or_b32 v70, v66, s12, v0
	v_or3_b32 v0, v67, v181, v70
	v_lshl_add_u64 v[146:147], v[0:1], 1, s[46:47]
	v_or3_b32 v0, v70, v69, v68
	s_mov_b32 s4, 0x180000
	v_add3_u32 v0, v0, v181, s4
	v_lshl_add_u64 v[148:149], v[0:1], 1, s[46:47]
	global_load_dwordx2 v[192:193], v[148:149], off
	global_load_dwordx2 v[194:195], v[148:149], off offset:256
	global_load_dwordx2 v[196:197], v[148:149], off offset:512
	global_load_dwordx2 v[198:199], v[148:149], off offset:768
	global_load_dwordx2 v[200:201], v[148:149], off offset:1024
	global_load_dwordx2 v[202:203], v[148:149], off offset:1280
	global_load_dwordx2 v[204:205], v[148:149], off offset:1536
	global_load_dwordx2 v[206:207], v[148:149], off offset:1792
	global_load_dwordx2 v[208:209], v[148:149], off offset:2048
	global_load_dwordx2 v[210:211], v[148:149], off offset:2304
	global_load_dwordx2 v[212:213], v[148:149], off offset:2560
	global_load_dwordx2 v[214:215], v[148:149], off offset:2816
	global_load_dwordx2 v[216:217], v[148:149], off offset:3072
	global_load_dwordx2 v[218:219], v[148:149], off offset:3328
	global_load_dwordx2 v[220:221], v[148:149], off offset:3584
	global_load_dwordx2 v[222:223], v[148:149], off offset:3840
	s_add_i32 s5, s26, s33
	s_and_b32 s5, s5, 7
	s_lshl_b32 s5, s5, 8
	s_mov_b64 vcc, exec
	s_mov_b64 exec, 1
	v_mov_b32_e32 v66, s5
	v_mov_b32_e32 v67, 1
	global_atomic_add v240, v66, v67, s[34:35] sc0
	s_mov_b64 exec, vcc
	s_mov_b32 s100, 1
	s_waitcnt vmcnt(16)
	v_lshlrev_b32_e32 v66, 16, v192
	v_and_b32_e32 v67, 0xffff0000, v192
	v_lshlrev_b32_e32 v68, 16, v193
	v_and_b32_e32 v69, 0xffff0000, v193
	v_mul_f32_e32 v70, 0xbfb8aa3b, v66
	v_mul_f32_e32 v71, 0xbfb8aa3b, v67
	v_mul_f32_e32 v72, 0xbfb8aa3b, v68
	v_mul_f32_e32 v73, 0xbfb8aa3b, v69
	v_exp_f32_e32 v70, v70
	v_exp_f32_e32 v71, v71
	v_exp_f32_e32 v72, v72
	v_exp_f32_e32 v73, v73
	v_pk_mul_f32 v[50:51], v[50:51], v[66:67]
	v_pk_mul_f32 v[52:53], v[52:53], v[68:69]
	v_add_f32_e32 v70, 1.0, v70
	v_add_f32_e32 v71, 1.0, v71
	v_add_f32_e32 v72, 1.0, v72
	v_add_f32_e32 v73, 1.0, v73
	v_rcp_f32_e32 v70, v70
	v_rcp_f32_e32 v71, v71
	v_rcp_f32_e32 v72, v72
	v_rcp_f32_e32 v73, v73
	v_pk_mul_f32 v[50:51], v[50:51], v[70:71]
	v_pk_mul_f32 v[52:53], v[52:53], v[72:73]
	v_cvt_pk_bf16_f32 v50, v50, v51
	v_cvt_pk_bf16_f32 v51, v52, v53
	s_waitcnt vmcnt(15)
	v_lshlrev_b32_e32 v74, 16, v194
	v_and_b32_e32 v75, 0xffff0000, v194
	v_lshlrev_b32_e32 v76, 16, v195
	v_and_b32_e32 v77, 0xffff0000, v195
	v_mul_f32_e32 v78, 0xbfb8aa3b, v74
	v_mul_f32_e32 v79, 0xbfb8aa3b, v75
	v_mul_f32_e32 v80, 0xbfb8aa3b, v76
	v_mul_f32_e32 v81, 0xbfb8aa3b, v77
	v_exp_f32_e32 v78, v78
	v_exp_f32_e32 v79, v79
	v_exp_f32_e32 v80, v80
	v_exp_f32_e32 v81, v81
	v_pk_mul_f32 v[54:55], v[54:55], v[74:75]
	v_pk_mul_f32 v[56:57], v[56:57], v[76:77]
	v_add_f32_e32 v78, 1.0, v78
	v_add_f32_e32 v79, 1.0, v79
	v_add_f32_e32 v80, 1.0, v80
	v_add_f32_e32 v81, 1.0, v81
	v_rcp_f32_e32 v78, v78
	v_rcp_f32_e32 v79, v79
	v_rcp_f32_e32 v80, v80
	v_rcp_f32_e32 v81, v81
	v_pk_mul_f32 v[54:55], v[54:55], v[78:79]
	v_pk_mul_f32 v[56:57], v[56:57], v[80:81]
	v_cvt_pk_bf16_f32 v54, v54, v55
	v_cvt_pk_bf16_f32 v55, v56, v57
	s_waitcnt vmcnt(14)
	v_lshlrev_b32_e32 v66, 16, v196
	v_and_b32_e32 v67, 0xffff0000, v196
	v_lshlrev_b32_e32 v68, 16, v197
	v_and_b32_e32 v69, 0xffff0000, v197
	v_mul_f32_e32 v70, 0xbfb8aa3b, v66
	v_mul_f32_e32 v71, 0xbfb8aa3b, v67
	v_mul_f32_e32 v72, 0xbfb8aa3b, v68
	v_mul_f32_e32 v73, 0xbfb8aa3b, v69
	v_exp_f32_e32 v70, v70
	v_exp_f32_e32 v71, v71
	v_exp_f32_e32 v72, v72
	v_exp_f32_e32 v73, v73
	v_pk_mul_f32 v[58:59], v[58:59], v[66:67]
	v_pk_mul_f32 v[60:61], v[60:61], v[68:69]
	v_add_f32_e32 v70, 1.0, v70
	v_add_f32_e32 v71, 1.0, v71
	v_add_f32_e32 v72, 1.0, v72
	v_add_f32_e32 v73, 1.0, v73
	v_rcp_f32_e32 v70, v70
	v_rcp_f32_e32 v71, v71
	v_rcp_f32_e32 v72, v72
	v_rcp_f32_e32 v73, v73
	v_pk_mul_f32 v[58:59], v[58:59], v[70:71]
	v_pk_mul_f32 v[60:61], v[60:61], v[72:73]
	v_cvt_pk_bf16_f32 v58, v58, v59
	v_cvt_pk_bf16_f32 v59, v60, v61
	s_waitcnt vmcnt(13)
	v_lshlrev_b32_e32 v74, 16, v198
	v_and_b32_e32 v75, 0xffff0000, v198
	v_lshlrev_b32_e32 v76, 16, v199
	v_and_b32_e32 v77, 0xffff0000, v199
	v_mul_f32_e32 v78, 0xbfb8aa3b, v74
	v_mul_f32_e32 v79, 0xbfb8aa3b, v75
	v_mul_f32_e32 v80, 0xbfb8aa3b, v76
	v_mul_f32_e32 v81, 0xbfb8aa3b, v77
	v_exp_f32_e32 v78, v78
	v_exp_f32_e32 v79, v79
	v_exp_f32_e32 v80, v80
	v_exp_f32_e32 v81, v81
	v_pk_mul_f32 v[62:63], v[62:63], v[74:75]
	v_pk_mul_f32 v[64:65], v[64:65], v[76:77]
	v_add_f32_e32 v78, 1.0, v78
	v_add_f32_e32 v79, 1.0, v79
	v_add_f32_e32 v80, 1.0, v80
	v_add_f32_e32 v81, 1.0, v81
	v_rcp_f32_e32 v78, v78
	v_rcp_f32_e32 v79, v79
	v_rcp_f32_e32 v80, v80
	v_rcp_f32_e32 v81, v81
	v_pk_mul_f32 v[62:63], v[62:63], v[78:79]
	v_pk_mul_f32 v[64:65], v[64:65], v[80:81]
	v_cvt_pk_bf16_f32 v62, v62, v63
	v_cvt_pk_bf16_f32 v63, v64, v65
	s_waitcnt vmcnt(12)
; DI unsigned pk2(float a, float b) { f32x2 v = {a, b}; bf16v2 r = __builtin_convertvector(v, bf16v2); return __builtin_bit_cast(unsigned, r); }
; DI float bf_lo(unsigned u) { return __uint_as_float(u << 16); }
; DI float bf_hi(unsigned u) { return __uint_as_float(u & 0xffff0000u); }
; DI size_t zrowU(int row0, int NT) { return ((size_t)((row0 >> 8) * NT) << 16) + (size_t)((((row0 >> 7) & 1) << 15) | (((row0 >> 5) & 1) << 14) | (((row0 >> 6) & 1) << 11)); }
; DI unsigned zlaneRC(int r5, int col) { return (unsigned)(((col >> 8) << 16) | ((r5 >> 4) << 13) | (((col >> 7) & 1) << 12) | (((col >> 5) & 3) << 9) | (((col >> 3) & 3) << 7) | ((r5 & 15) << 3) | (col & 7)); }
; DI float silu_mul(float o, float g) { return o * g * __builtin_amdgcn_rcpf(1.0f + __builtin_amdgcn_exp2f(g * -1.4426950408889634f)); }
; DI void attnB_item(bf16_t* z, int hh, int qs, LAS bf16_t* vs, int lane) {
;     ...
;     if (!metaq || c < NMETA) {
;         bf16_t* orow = z + zrowU(qrow0, 32) + zlaneRC(c, hh * 128 + 4 * h);
;         const bf16_t* grow = z + zrowU(qrow0, 32) + zlaneRC(c, 6144 + hh * 128 + 4 * h);
; #pragma unroll
;         for (int dt = 0; dt < 4; ++dt)
; #pragma unroll
;             for (int g = 0; g < 4; ++g) {
;                 const int d0 = (dt << 9) | (g << 7);
;                 const u32x2 gv = *(const u32x2*)(grow + d0);
;                 u32x2 o; o.x = pk2(silu_mul(acc[dt][4 * g], bf_lo(gv.x)), silu_mul(acc[dt][4 * g + 1], bf_hi(gv.x)));
;                 o.y = pk2(silu_mul(acc[dt][4 * g + 2], bf_lo(gv.y)), silu_mul(acc[dt][4 * g + 3], bf_hi(gv.y)));
;                 *(u32x2*)(orow + d0) = o;
;             }
;     }
	v_lshlrev_b32_e32 v66, 16, v200
	v_and_b32_e32 v67, 0xffff0000, v200
	v_lshlrev_b32_e32 v68, 16, v201
	v_and_b32_e32 v69, 0xffff0000, v201
	v_mul_f32_e32 v70, 0xbfb8aa3b, v66
	v_mul_f32_e32 v71, 0xbfb8aa3b, v67
	v_mul_f32_e32 v72, 0xbfb8aa3b, v68
	v_mul_f32_e32 v73, 0xbfb8aa3b, v69
	v_exp_f32_e32 v70, v70
	v_exp_f32_e32 v71, v71
	v_exp_f32_e32 v72, v72
	v_exp_f32_e32 v73, v73
	v_pk_mul_f32 v[34:35], v[34:35], v[66:67]
	v_pk_mul_f32 v[36:37], v[36:37], v[68:69]
	v_add_f32_e32 v70, 1.0, v70
	v_add_f32_e32 v71, 1.0, v71
	v_add_f32_e32 v72, 1.0, v72
	v_add_f32_e32 v73, 1.0, v73
	v_rcp_f32_e32 v70, v70
	v_rcp_f32_e32 v71, v71
	v_rcp_f32_e32 v72, v72
	v_rcp_f32_e32 v73, v73
	v_pk_mul_f32 v[34:35], v[34:35], v[70:71]
	v_pk_mul_f32 v[36:37], v[36:37], v[72:73]
	v_cvt_pk_bf16_f32 v34, v34, v35
	v_cvt_pk_bf16_f32 v35, v36, v37
	s_waitcnt vmcnt(11)
	v_lshlrev_b32_e32 v74, 16, v202
	v_and_b32_e32 v75, 0xffff0000, v202
	v_lshlrev_b32_e32 v76, 16, v203
	v_and_b32_e32 v77, 0xffff0000, v203
	v_mul_f32_e32 v78, 0xbfb8aa3b, v74
	v_mul_f32_e32 v79, 0xbfb8aa3b, v75
	v_mul_f32_e32 v80, 0xbfb8aa3b, v76
	v_mul_f32_e32 v81, 0xbfb8aa3b, v77
	v_exp_f32_e32 v78, v78
	v_exp_f32_e32 v79, v79
	v_exp_f32_e32 v80, v80
	v_exp_f32_e32 v81, v81
	v_pk_mul_f32 v[38:39], v[38:39], v[74:75]
	v_pk_mul_f32 v[40:41], v[40:41], v[76:77]
	v_add_f32_e32 v78, 1.0, v78
	v_add_f32_e32 v79, 1.0, v79
	v_add_f32_e32 v80, 1.0, v80
	v_add_f32_e32 v81, 1.0, v81
	v_rcp_f32_e32 v78, v78
	v_rcp_f32_e32 v79, v79
	v_rcp_f32_e32 v80, v80
	v_rcp_f32_e32 v81, v81
	v_pk_mul_f32 v[38:39], v[38:39], v[78:79]
	v_pk_mul_f32 v[40:41], v[40:41], v[80:81]
	v_cvt_pk_bf16_f32 v38, v38, v39
	v_cvt_pk_bf16_f32 v39, v40, v41
	s_waitcnt vmcnt(10)
	v_lshlrev_b32_e32 v66, 16, v204
	v_and_b32_e32 v67, 0xffff0000, v204
	v_lshlrev_b32_e32 v68, 16, v205
	v_and_b32_e32 v69, 0xffff0000, v205
	v_mul_f32_e32 v70, 0xbfb8aa3b, v66
	v_mul_f32_e32 v71, 0xbfb8aa3b, v67
	v_mul_f32_e32 v72, 0xbfb8aa3b, v68
	v_mul_f32_e32 v73, 0xbfb8aa3b, v69
	v_exp_f32_e32 v70, v70
	v_exp_f32_e32 v71, v71
	v_exp_f32_e32 v72, v72
	v_exp_f32_e32 v73, v73
	v_pk_mul_f32 v[42:43], v[42:43], v[66:67]
	v_pk_mul_f32 v[44:45], v[44:45], v[68:69]
	v_add_f32_e32 v70, 1.0, v70
	v_add_f32_e32 v71, 1.0, v71
	v_add_f32_e32 v72, 1.0, v72
	v_add_f32_e32 v73, 1.0, v73
	v_rcp_f32_e32 v70, v70
	v_rcp_f32_e32 v71, v71
	v_rcp_f32_e32 v72, v72
	v_rcp_f32_e32 v73, v73
	v_pk_mul_f32 v[42:43], v[42:43], v[70:71]
	v_pk_mul_f32 v[44:45], v[44:45], v[72:73]
	v_cvt_pk_bf16_f32 v42, v42, v43
	v_cvt_pk_bf16_f32 v43, v44, v45
	s_waitcnt vmcnt(9)
	v_lshlrev_b32_e32 v74, 16, v206
	v_and_b32_e32 v75, 0xffff0000, v206
	v_lshlrev_b32_e32 v76, 16, v207
	v_and_b32_e32 v77, 0xffff0000, v207
	v_mul_f32_e32 v78, 0xbfb8aa3b, v74
	v_mul_f32_e32 v79, 0xbfb8aa3b, v75
	v_mul_f32_e32 v80, 0xbfb8aa3b, v76
	v_mul_f32_e32 v81, 0xbfb8aa3b, v77
	v_exp_f32_e32 v78, v78
	v_exp_f32_e32 v79, v79
	v_exp_f32_e32 v80, v80
	v_exp_f32_e32 v81, v81
	v_pk_mul_f32 v[46:47], v[46:47], v[74:75]
	v_pk_mul_f32 v[48:49], v[48:49], v[76:77]
	v_add_f32_e32 v78, 1.0, v78
	v_add_f32_e32 v79, 1.0, v79
	v_add_f32_e32 v80, 1.0, v80
	v_add_f32_e32 v81, 1.0, v81
	v_rcp_f32_e32 v78, v78
	v_rcp_f32_e32 v79, v79
	v_rcp_f32_e32 v80, v80
	v_rcp_f32_e32 v81, v81
	v_pk_mul_f32 v[46:47], v[46:47], v[78:79]
	v_pk_mul_f32 v[48:49], v[48:49], v[80:81]
	v_cvt_pk_bf16_f32 v46, v46, v47
	v_cvt_pk_bf16_f32 v47, v48, v49
	s_waitcnt vmcnt(8)
	v_lshlrev_b32_e32 v66, 16, v208
	v_and_b32_e32 v67, 0xffff0000, v208
	v_lshlrev_b32_e32 v68, 16, v209
	v_and_b32_e32 v69, 0xffff0000, v209
	v_mul_f32_e32 v70, 0xbfb8aa3b, v66
	v_mul_f32_e32 v71, 0xbfb8aa3b, v67
	v_mul_f32_e32 v72, 0xbfb8aa3b, v68
	v_mul_f32_e32 v73, 0xbfb8aa3b, v69
	v_exp_f32_e32 v70, v70
	v_exp_f32_e32 v71, v71
	v_exp_f32_e32 v72, v72
	v_exp_f32_e32 v73, v73
	v_pk_mul_f32 v[18:19], v[18:19], v[66:67]
	v_pk_mul_f32 v[20:21], v[20:21], v[68:69]
	v_add_f32_e32 v70, 1.0, v70
	v_add_f32_e32 v71, 1.0, v71
	v_add_f32_e32 v72, 1.0, v72
	v_add_f32_e32 v73, 1.0, v73
	v_rcp_f32_e32 v70, v70
	v_rcp_f32_e32 v71, v71
	v_rcp_f32_e32 v72, v72
	v_rcp_f32_e32 v73, v73
	v_pk_mul_f32 v[18:19], v[18:19], v[70:71]
	v_pk_mul_f32 v[20:21], v[20:21], v[72:73]
	v_cvt_pk_bf16_f32 v18, v18, v19
	v_cvt_pk_bf16_f32 v19, v20, v21
	s_waitcnt vmcnt(7)
	v_lshlrev_b32_e32 v74, 16, v210
	v_and_b32_e32 v75, 0xffff0000, v210
	v_lshlrev_b32_e32 v76, 16, v211
	v_and_b32_e32 v77, 0xffff0000, v211
	v_mul_f32_e32 v78, 0xbfb8aa3b, v74
	v_mul_f32_e32 v79, 0xbfb8aa3b, v75
	v_mul_f32_e32 v80, 0xbfb8aa3b, v76
	v_mul_f32_e32 v81, 0xbfb8aa3b, v77
	v_exp_f32_e32 v78, v78
	v_exp_f32_e32 v79, v79
	v_exp_f32_e32 v80, v80
	v_exp_f32_e32 v81, v81
	v_pk_mul_f32 v[22:23], v[22:23], v[74:75]
	v_pk_mul_f32 v[24:25], v[24:25], v[76:77]
	v_add_f32_e32 v78, 1.0, v78
	v_add_f32_e32 v79, 1.0, v79
	v_add_f32_e32 v80, 1.0, v80
	v_add_f32_e32 v81, 1.0, v81
	v_rcp_f32_e32 v78, v78
	v_rcp_f32_e32 v79, v79
	v_rcp_f32_e32 v80, v80
	v_rcp_f32_e32 v81, v81
	v_pk_mul_f32 v[22:23], v[22:23], v[78:79]
	v_pk_mul_f32 v[24:25], v[24:25], v[80:81]
	v_cvt_pk_bf16_f32 v22, v22, v23
	v_cvt_pk_bf16_f32 v23, v24, v25
	s_waitcnt vmcnt(6)
	v_lshlrev_b32_e32 v66, 16, v212
	v_and_b32_e32 v67, 0xffff0000, v212
	v_lshlrev_b32_e32 v68, 16, v213
	v_and_b32_e32 v69, 0xffff0000, v213
	v_mul_f32_e32 v70, 0xbfb8aa3b, v66
	v_mul_f32_e32 v71, 0xbfb8aa3b, v67
	v_mul_f32_e32 v72, 0xbfb8aa3b, v68
	v_mul_f32_e32 v73, 0xbfb8aa3b, v69
	v_exp_f32_e32 v70, v70
	v_exp_f32_e32 v71, v71
	v_exp_f32_e32 v72, v72
	v_exp_f32_e32 v73, v73
	v_pk_mul_f32 v[26:27], v[26:27], v[66:67]
	v_pk_mul_f32 v[28:29], v[28:29], v[68:69]
	v_add_f32_e32 v70, 1.0, v70
	v_add_f32_e32 v71, 1.0, v71
	v_add_f32_e32 v72, 1.0, v72
	v_add_f32_e32 v73, 1.0, v73
	v_rcp_f32_e32 v70, v70
	v_rcp_f32_e32 v71, v71
	v_rcp_f32_e32 v72, v72
	v_rcp_f32_e32 v73, v73
	v_pk_mul_f32 v[26:27], v[26:27], v[70:71]
	v_pk_mul_f32 v[28:29], v[28:29], v[72:73]
	v_cvt_pk_bf16_f32 v26, v26, v27
	v_cvt_pk_bf16_f32 v27, v28, v29
	s_waitcnt vmcnt(5)
; DI unsigned pk2(float a, float b) { f32x2 v = {a, b}; bf16v2 r = __builtin_convertvector(v, bf16v2); return __builtin_bit_cast(unsigned, r); }
; DI float bf_lo(unsigned u) { return __uint_as_float(u << 16); }
; DI float bf_hi(unsigned u) { return __uint_as_float(u & 0xffff0000u); }
; DI size_t zrowU(int row0, int NT) { return ((size_t)((row0 >> 8) * NT) << 16) + (size_t)((((row0 >> 7) & 1) << 15) | (((row0 >> 5) & 1) << 14) | (((row0 >> 6) & 1) << 11)); }
; DI unsigned zlaneRC(int r5, int col) { return (unsigned)(((col >> 8) << 16) | ((r5 >> 4) << 13) | (((col >> 7) & 1) << 12) | (((col >> 5) & 3) << 9) | (((col >> 3) & 3) << 7) | ((r5 & 15) << 3) | (col & 7)); }
; DI float silu_mul(float o, float g) { return o * g * __builtin_amdgcn_rcpf(1.0f + __builtin_amdgcn_exp2f(g * -1.4426950408889634f)); }
; DI void attnB_item(bf16_t* z, int hh, int qs, LAS bf16_t* vs, int lane) {
;     ...
;     if (!metaq || c < NMETA) {
;         bf16_t* orow = z + zrowU(qrow0, 32) + zlaneRC(c, hh * 128 + 4 * h);
;         const bf16_t* grow = z + zrowU(qrow0, 32) + zlaneRC(c, 6144 + hh * 128 + 4 * h);
; #pragma unroll
;         for (int dt = 0; dt < 4; ++dt)
; #pragma unroll
;             for (int g = 0; g < 4; ++g) {
;                 const int d0 = (dt << 9) | (g << 7);
;                 const u32x2 gv = *(const u32x2*)(grow + d0);
;                 u32x2 o; o.x = pk2(silu_mul(acc[dt][4 * g], bf_lo(gv.x)), silu_mul(acc[dt][4 * g + 1], bf_hi(gv.x)));
;                 o.y = pk2(silu_mul(acc[dt][4 * g + 2], bf_lo(gv.y)), silu_mul(acc[dt][4 * g + 3], bf_hi(gv.y)));
;                 *(u32x2*)(orow + d0) = o;
;             }
;     }
	v_lshlrev_b32_e32 v74, 16, v214
	v_and_b32_e32 v75, 0xffff0000, v214
	v_lshlrev_b32_e32 v76, 16, v215
	v_and_b32_e32 v77, 0xffff0000, v215
	v_mul_f32_e32 v78, 0xbfb8aa3b, v74
	v_mul_f32_e32 v79, 0xbfb8aa3b, v75
	v_mul_f32_e32 v80, 0xbfb8aa3b, v76
	v_mul_f32_e32 v81, 0xbfb8aa3b, v77
	v_exp_f32_e32 v78, v78
	v_exp_f32_e32 v79, v79
	v_exp_f32_e32 v80, v80
	v_exp_f32_e32 v81, v81
	v_pk_mul_f32 v[30:31], v[30:31], v[74:75]
	v_pk_mul_f32 v[32:33], v[32:33], v[76:77]
	v_add_f32_e32 v78, 1.0, v78
	v_add_f32_e32 v79, 1.0, v79
	v_add_f32_e32 v80, 1.0, v80
	v_add_f32_e32 v81, 1.0, v81
	v_rcp_f32_e32 v78, v78
	v_rcp_f32_e32 v79, v79
	v_rcp_f32_e32 v80, v80
	v_rcp_f32_e32 v81, v81
	v_pk_mul_f32 v[30:31], v[30:31], v[78:79]
	v_pk_mul_f32 v[32:33], v[32:33], v[80:81]
	v_cvt_pk_bf16_f32 v30, v30, v31
	v_cvt_pk_bf16_f32 v31, v32, v33
	s_waitcnt vmcnt(4)
	v_lshlrev_b32_e32 v66, 16, v216
	v_and_b32_e32 v67, 0xffff0000, v216
	v_lshlrev_b32_e32 v68, 16, v217
	v_and_b32_e32 v69, 0xffff0000, v217
	v_mul_f32_e32 v70, 0xbfb8aa3b, v66
	v_mul_f32_e32 v71, 0xbfb8aa3b, v67
	v_mul_f32_e32 v72, 0xbfb8aa3b, v68
	v_mul_f32_e32 v73, 0xbfb8aa3b, v69
	v_exp_f32_e32 v70, v70
	v_exp_f32_e32 v71, v71
	v_exp_f32_e32 v72, v72
	v_exp_f32_e32 v73, v73
	v_pk_mul_f32 v[2:3], v[2:3], v[66:67]
	v_pk_mul_f32 v[4:5], v[4:5], v[68:69]
	v_add_f32_e32 v70, 1.0, v70
	v_add_f32_e32 v71, 1.0, v71
	v_add_f32_e32 v72, 1.0, v72
	v_add_f32_e32 v73, 1.0, v73
	v_rcp_f32_e32 v70, v70
	v_rcp_f32_e32 v71, v71
	v_rcp_f32_e32 v72, v72
	v_rcp_f32_e32 v73, v73
	v_pk_mul_f32 v[2:3], v[2:3], v[70:71]
	v_pk_mul_f32 v[4:5], v[4:5], v[72:73]
	v_cvt_pk_bf16_f32 v2, v2, v3
	v_cvt_pk_bf16_f32 v3, v4, v5
	s_waitcnt vmcnt(3)
	v_lshlrev_b32_e32 v74, 16, v218
	v_and_b32_e32 v75, 0xffff0000, v218
	v_lshlrev_b32_e32 v76, 16, v219
	v_and_b32_e32 v77, 0xffff0000, v219
	v_mul_f32_e32 v78, 0xbfb8aa3b, v74
	v_mul_f32_e32 v79, 0xbfb8aa3b, v75
	v_mul_f32_e32 v80, 0xbfb8aa3b, v76
	v_mul_f32_e32 v81, 0xbfb8aa3b, v77
	v_exp_f32_e32 v78, v78
	v_exp_f32_e32 v79, v79
	v_exp_f32_e32 v80, v80
	v_exp_f32_e32 v81, v81
	v_pk_mul_f32 v[6:7], v[6:7], v[74:75]
	v_pk_mul_f32 v[8:9], v[8:9], v[76:77]
	v_add_f32_e32 v78, 1.0, v78
	v_add_f32_e32 v79, 1.0, v79
	v_add_f32_e32 v80, 1.0, v80
	v_add_f32_e32 v81, 1.0, v81
	v_rcp_f32_e32 v78, v78
	v_rcp_f32_e32 v79, v79
	v_rcp_f32_e32 v80, v80
	v_rcp_f32_e32 v81, v81
	v_pk_mul_f32 v[6:7], v[6:7], v[78:79]
	v_pk_mul_f32 v[8:9], v[8:9], v[80:81]
	v_cvt_pk_bf16_f32 v6, v6, v7
	v_cvt_pk_bf16_f32 v7, v8, v9
	s_waitcnt vmcnt(2)
	v_lshlrev_b32_e32 v66, 16, v220
	v_and_b32_e32 v67, 0xffff0000, v220
	v_lshlrev_b32_e32 v68, 16, v221
	v_and_b32_e32 v69, 0xffff0000, v221
	v_mul_f32_e32 v70, 0xbfb8aa3b, v66
	v_mul_f32_e32 v71, 0xbfb8aa3b, v67
	v_mul_f32_e32 v72, 0xbfb8aa3b, v68
	v_mul_f32_e32 v73, 0xbfb8aa3b, v69
	v_exp_f32_e32 v70, v70
	v_exp_f32_e32 v71, v71
	v_exp_f32_e32 v72, v72
	v_exp_f32_e32 v73, v73
	v_pk_mul_f32 v[10:11], v[10:11], v[66:67]
	v_pk_mul_f32 v[12:13], v[12:13], v[68:69]
	v_add_f32_e32 v70, 1.0, v70
	v_add_f32_e32 v71, 1.0, v71
	v_add_f32_e32 v72, 1.0, v72
	v_add_f32_e32 v73, 1.0, v73
	v_rcp_f32_e32 v70, v70
	v_rcp_f32_e32 v71, v71
	v_rcp_f32_e32 v72, v72
	v_rcp_f32_e32 v73, v73
	v_pk_mul_f32 v[10:11], v[10:11], v[70:71]
	v_pk_mul_f32 v[12:13], v[12:13], v[72:73]
	v_cvt_pk_bf16_f32 v10, v10, v11
	v_cvt_pk_bf16_f32 v11, v12, v13
	s_waitcnt vmcnt(1)
	v_lshlrev_b32_e32 v74, 16, v222
	v_and_b32_e32 v75, 0xffff0000, v222
	v_lshlrev_b32_e32 v76, 16, v223
	v_and_b32_e32 v77, 0xffff0000, v223
	v_mul_f32_e32 v78, 0xbfb8aa3b, v74
	v_mul_f32_e32 v79, 0xbfb8aa3b, v75
	v_mul_f32_e32 v80, 0xbfb8aa3b, v76
	v_mul_f32_e32 v81, 0xbfb8aa3b, v77
	v_exp_f32_e32 v78, v78
	v_exp_f32_e32 v79, v79
	v_exp_f32_e32 v80, v80
	v_exp_f32_e32 v81, v81
	v_pk_mul_f32 v[14:15], v[14:15], v[74:75]
	v_pk_mul_f32 v[16:17], v[16:17], v[76:77]
	v_add_f32_e32 v78, 1.0, v78
	v_add_f32_e32 v79, 1.0, v79
	v_add_f32_e32 v80, 1.0, v80
	v_add_f32_e32 v81, 1.0, v81
	v_rcp_f32_e32 v78, v78
	v_rcp_f32_e32 v79, v79
	v_rcp_f32_e32 v80, v80
	v_rcp_f32_e32 v81, v81
	v_pk_mul_f32 v[14:15], v[14:15], v[78:79]
	v_pk_mul_f32 v[16:17], v[16:17], v[80:81]
	v_cvt_pk_bf16_f32 v14, v14, v15
	v_cvt_pk_bf16_f32 v15, v16, v17
	global_store_dwordx2 v[146:147], v[50:51], off
	global_store_dwordx2 v[146:147], v[54:55], off offset:256
	global_store_dwordx2 v[146:147], v[58:59], off offset:512
	global_store_dwordx2 v[146:147], v[62:63], off offset:768
	global_store_dwordx2 v[146:147], v[34:35], off offset:1024
	global_store_dwordx2 v[146:147], v[38:39], off offset:1280
	global_store_dwordx2 v[146:147], v[42:43], off offset:1536
	global_store_dwordx2 v[146:147], v[46:47], off offset:1792
	global_store_dwordx2 v[146:147], v[18:19], off offset:2048
	global_store_dwordx2 v[146:147], v[22:23], off offset:2304
	global_store_dwordx2 v[146:147], v[26:27], off offset:2560
	global_store_dwordx2 v[146:147], v[30:31], off offset:2816
	global_store_dwordx2 v[146:147], v[2:3], off offset:3072
	global_store_dwordx2 v[146:147], v[6:7], off offset:3328
	global_store_dwordx2 v[146:147], v[10:11], off offset:3584
	global_store_dwordx2 v[146:147], v[14:15], off offset:3840
	s_branch .LBB0_130

; DI unsigned pk2(float a, float b) { f32x2 v = {a, b}; bf16v2 r = __builtin_convertvector(v, bf16v2); return __builtin_bit_cast(unsigned, r); }
; DI float bf_lo(unsigned u) { return __uint_as_float(u << 16); }
; DI float bf_hi(unsigned u) { return __uint_as_float(u & 0xffff0000u); }
; DI size_t zrowU(int row0, int NT) { return ((size_t)((row0 >> 8) * NT) << 16) + (size_t)((((row0 >> 7) & 1) << 15) | (((row0 >> 5) & 1) << 14) | (((row0 >> 6) & 1) << 11)); }
; DI unsigned zlaneRC(int r5, int col) { return (unsigned)(((col >> 8) << 16) | ((r5 >> 4) << 13) | (((col >> 7) & 1) << 12) | (((col >> 5) & 3) << 9) | (((col >> 3) & 3) << 7) | ((r5 & 15) << 3) | (col & 7)); }
; DI void attnA_item(bf16_t* z, const float* sinks, int hp, int qs, LAS bf16_t* vs, const LAS float* btab, int lane) {
;     ...
;     if (!metaq || c < NMETA) {
; #pragma unroll
;         for (int u = 0; u < 2; ++u) {
;             const float inv = 1.0f / l[u];
;             bf16_t* orow = z + zrowU(qrow0, 18) + zlaneRC(c, (2 * hp + u) * 64 + 4 * h);
;             const bf16_t* grow = z + zrowU(qrow0, 18) + zlaneRC(c, 2560 + (2 * hp + u) * 64 + 4 * h);
; #pragma unroll
;             for (int dt = 0; dt < 2; ++dt)
; #pragma unroll
;                 for (int g = 0; g < 4; ++g) {
;                     const int d0 = (dt << 9) | (g << 7);
;                     const u32x2 gv = *(const u32x2*)(grow + d0);
;                     u32x2 o; o.x = pk2(silu_mul(acc[u][dt][4 * g] * inv, bf_lo(gv.x)), silu_mul(acc[u][dt][4 * g + 1] * inv, bf_hi(gv.x)));
;                     o.y = pk2(silu_mul(acc[u][dt][4 * g + 2] * inv, bf_lo(gv.y)), silu_mul(acc[u][dt][4 * g + 3] * inv, bf_hi(gv.y)));
;                     *(u32x2*)(orow + d0) = o;
;                 }
;         }
;     }
; DI bool attn_next(AttnQueue& q, int lane0, int& qs, int& hd) {
;     for (;;) {
;         if (q.cur >= 8) return false;
;         const int xq = (q.x + q.cur) & 7;
;         const int nqs = NQS / 8 + (xq == 7 ? 1 : 0);
;         unsigned n = 0;
;         if (lane0) n = __hip_atomic_fetch_add(q.heads + 64 * xq, 1u, __ATOMIC_RELAXED, __HIP_MEMORY_SCOPE_AGENT);
;         n = (unsigned)__builtin_amdgcn_readfirstlane((int)n);
;         if (n < (unsigned)(nqs * 16)) { qs = (NQS / 8) * xq + (int)(n >> 4); hd = (int)(n & 15u); return true; }
.LBB0_211:
	v_cmp_gt_u32_e32 vcc, 16, v127
	s_xor_b64 s[4:5], s[68:69], -1
	s_or_b64 s[4:5], s[4:5], vcc
	s_and_saveexec_b64 s[6:7], s[4:5]
	s_xor_b64 s[36:37], exec, s[6:7]
	s_cbranch_execz .LBB0_177
	v_div_scale_f32 v0, s[4:5], v75, v75, 1.0
	v_rcp_f32_e32 v130, v0
	v_and_b32_e32 v134, 4, v125
	v_add_u32_e32 v135, 0xa00, v125
	v_fma_f32 v148, -v0, v130, 1.0
	v_fmac_f32_e32 v130, v148, v130
	v_div_scale_f32 v148, vcc, 1.0, v75, 1.0
	v_mul_f32_e32 v149, v148, v130
	v_fma_f32 v150, -v0, v149, v148
	v_fmac_f32_e32 v149, v150, v130
	v_fma_f32 v0, -v0, v149, v148
	v_div_fmas_f32 v0, v0, v130, v149
	v_div_fixup_f32 v130, v0, v75, 1.0
	v_add_u32_e32 v0, s27, v125
	v_lshlrev_b32_e32 v136, 8, v0
	v_lshlrev_b32_e32 v0, 5, v0
	v_lshlrev_b32_e32 v137, 6, v126
	v_and_b32_e32 v136, 0xffff0000, v136
	v_and_b32_e32 v0, 0x1000, v0
	v_and_b32_e32 v146, 0x780, v137
	v_or3_b32 v0, v0, v136, v146
	v_or3_b32 v0, v0, v134, v124
	v_lshl_add_u64 v[138:139], v[0:1], 1, s[0:1]
	v_add_u32_e32 v0, s27, v135
	v_lshlrev_b32_e32 v147, 8, v0
	v_lshlrev_b32_e32 v0, 5, v0
	v_and_b32_e32 v147, 0xffff0000, v147
	v_and_b32_e32 v0, 0x1000, v0
	v_or3_b32 v0, v0, v147, v146
	v_or3_b32 v0, v0, v134, v124
	v_lshl_add_u64 v[140:141], v[0:1], 1, s[0:1]
	global_load_dwordx2 v[178:179], v[140:141], off
	global_load_dwordx2 v[180:181], v[140:141], off offset:256
	global_load_dwordx2 v[182:183], v[140:141], off offset:512
	global_load_dwordx2 v[184:185], v[140:141], off offset:768
	global_load_dwordx2 v[186:187], v[140:141], off offset:1024
	global_load_dwordx2 v[188:189], v[140:141], off offset:1280
	global_load_dwordx2 v[190:191], v[140:141], off offset:1536
	global_load_dwordx2 v[192:193], v[140:141], off offset:1792
	v_div_scale_f32 v0, s[4:5], v74, v74, 1.0
	s_or_b32 s4, s27, 64
	v_rcp_f32_e32 v132, v0
	s_nop 0
	v_fma_f32 v148, -v0, v132, 1.0
	v_fmac_f32_e32 v132, v148, v132
	v_div_scale_f32 v148, vcc, 1.0, v74, 1.0
	v_mul_f32_e32 v149, v148, v132
	v_fma_f32 v150, -v0, v149, v148
	v_fmac_f32_e32 v149, v150, v132
	v_fma_f32 v0, -v0, v149, v148
	v_div_fmas_f32 v0, v0, v132, v149
	v_div_fixup_f32 v132, v0, v74, 1.0
	v_add_u32_e32 v0, s4, v125
	v_lshlrev_b32_e32 v136, 8, v0
	v_lshlrev_b32_e32 v137, 5, v0
	v_lshlrev_b32_e32 v0, 4, v0
	v_and_b32_e32 v136, 0xffff0000, v136
	v_and_b32_e32 v137, 0x1000, v137
	v_and_b32_e32 v0, 0x780, v0
	v_or3_b32 v0, v137, v136, v0
	v_or3_b32 v0, v0, v134, v124
	v_lshl_add_u64 v[142:143], v[0:1], 1, s[0:1]
	v_add_u32_e32 v0, s4, v135
	v_lshlrev_b32_e32 v136, 8, v0
	v_lshlrev_b32_e32 v147, 5, v0
	v_lshlrev_b32_e32 v0, 4, v0
	v_and_b32_e32 v136, 0xffff0000, v136
	v_and_b32_e32 v147, 0x1000, v147
	v_and_b32_e32 v0, 0x780, v0
	v_or3_b32 v0, v147, v136, v0
	v_or3_b32 v0, v0, v134, v124
	v_lshl_add_u64 v[144:145], v[0:1], 1, s[0:1]
	global_load_dwordx2 v[194:195], v[144:145], off
	global_load_dwordx2 v[196:197], v[144:145], off offset:256
	global_load_dwordx2 v[198:199], v[144:145], off offset:512
	global_load_dwordx2 v[200:201], v[144:145], off offset:768
	global_load_dwordx2 v[202:203], v[144:145], off offset:1024
	global_load_dwordx2 v[204:205], v[144:145], off offset:1280
	global_load_dwordx2 v[206:207], v[144:145], off offset:1536
	global_load_dwordx2 v[208:209], v[144:145], off offset:1792
	s_add_i32 s5, s26, s33
	s_and_b32 s5, s5, 7
	s_lshl_b32 s5, s5, 8
	s_mov_b64 vcc, exec
	s_mov_b64 exec, 1
	v_mov_b32_e32 v210, s5
	v_mov_b32_e32 v211, 1
	global_atomic_add v240, v210, v211, s[34:35] sc0
	s_mov_b64 exec, vcc
	s_mov_b32 s100, 1
	v_pk_mul_f32 v[50:51], v[130:131], v[50:51] op_sel_hi:[0,1]
	v_pk_mul_f32 v[52:53], v[130:131], v[52:53] op_sel_hi:[0,1]
	v_pk_mul_f32 v[54:55], v[130:131], v[54:55] op_sel_hi:[0,1]
	v_pk_mul_f32 v[56:57], v[130:131], v[56:57] op_sel_hi:[0,1]
	v_pk_mul_f32 v[58:59], v[130:131], v[58:59] op_sel_hi:[0,1]
	v_pk_mul_f32 v[60:61], v[130:131], v[60:61] op_sel_hi:[0,1]
	v_pk_mul_f32 v[62:63], v[130:131], v[62:63] op_sel_hi:[0,1]
	v_pk_mul_f32 v[64:65], v[130:131], v[64:65] op_sel_hi:[0,1]
	v_pk_mul_f32 v[34:35], v[130:131], v[34:35] op_sel_hi:[0,1]
	v_pk_mul_f32 v[36:37], v[130:131], v[36:37] op_sel_hi:[0,1]
	v_pk_mul_f32 v[38:39], v[130:131], v[38:39] op_sel_hi:[0,1]
	v_pk_mul_f32 v[40:41], v[130:131], v[40:41] op_sel_hi:[0,1]
	v_pk_mul_f32 v[42:43], v[130:131], v[42:43] op_sel_hi:[0,1]
	v_pk_mul_f32 v[44:45], v[130:131], v[44:45] op_sel_hi:[0,1]
	v_pk_mul_f32 v[46:47], v[130:131], v[46:47] op_sel_hi:[0,1]
	v_pk_mul_f32 v[48:49], v[130:131], v[48:49] op_sel_hi:[0,1]
	v_pk_mul_f32 v[18:19], v[132:133], v[18:19] op_sel_hi:[0,1]
	v_pk_mul_f32 v[20:21], v[132:133], v[20:21] op_sel_hi:[0,1]
	v_pk_mul_f32 v[22:23], v[132:133], v[22:23] op_sel_hi:[0,1]
	v_pk_mul_f32 v[24:25], v[132:133], v[24:25] op_sel_hi:[0,1]
	v_pk_mul_f32 v[26:27], v[132:133], v[26:27] op_sel_hi:[0,1]
	v_pk_mul_f32 v[28:29], v[132:133], v[28:29] op_sel_hi:[0,1]
	v_pk_mul_f32 v[30:31], v[132:133], v[30:31] op_sel_hi:[0,1]
	v_pk_mul_f32 v[32:33], v[132:133], v[32:33] op_sel_hi:[0,1]
	v_pk_mul_f32 v[2:3], v[132:133], v[2:3] op_sel_hi:[0,1]
	v_pk_mul_f32 v[4:5], v[132:133], v[4:5] op_sel_hi:[0,1]
	v_pk_mul_f32 v[6:7], v[132:133], v[6:7] op_sel_hi:[0,1]
	v_pk_mul_f32 v[8:9], v[132:133], v[8:9] op_sel_hi:[0,1]
	v_pk_mul_f32 v[10:11], v[132:133], v[10:11] op_sel_hi:[0,1]
	v_pk_mul_f32 v[12:13], v[132:133], v[12:13] op_sel_hi:[0,1]
	v_pk_mul_f32 v[14:15], v[132:133], v[14:15] op_sel_hi:[0,1]
	v_pk_mul_f32 v[16:17], v[132:133], v[16:17] op_sel_hi:[0,1]
	s_waitcnt vmcnt(16)
; DI unsigned pk2(float a, float b) { f32x2 v = {a, b}; bf16v2 r = __builtin_convertvector(v, bf16v2); return __builtin_bit_cast(unsigned, r); }
; DI float bf_lo(unsigned u) { return __uint_as_float(u << 16); }
; DI float bf_hi(unsigned u) { return __uint_as_float(u & 0xffff0000u); }
; DI size_t zrowU(int row0, int NT) { return ((size_t)((row0 >> 8) * NT) << 16) + (size_t)((((row0 >> 7) & 1) << 15) | (((row0 >> 5) & 1) << 14) | (((row0 >> 6) & 1) << 11)); }
; DI unsigned zlaneRC(int r5, int col) { return (unsigned)(((col >> 8) << 16) | ((r5 >> 4) << 13) | (((col >> 7) & 1) << 12) | (((col >> 5) & 3) << 9) | (((col >> 3) & 3) << 7) | ((r5 & 15) << 3) | (col & 7)); }
; DI float silu_mul(float o, float g) { return o * g * __builtin_amdgcn_rcpf(1.0f + __builtin_amdgcn_exp2f(g * -1.4426950408889634f)); }
; DI void attnA_item(bf16_t* z, const float* sinks, int hp, int qs, LAS bf16_t* vs, const LAS float* btab, int lane) {
;     ...
;     if (!metaq || c < NMETA) {
; #pragma unroll
;         for (int u = 0; u < 2; ++u) {
;             const float inv = 1.0f / l[u];
;             bf16_t* orow = z + zrowU(qrow0, 18) + zlaneRC(c, (2 * hp + u) * 64 + 4 * h);
;             const bf16_t* grow = z + zrowU(qrow0, 18) + zlaneRC(c, 2560 + (2 * hp + u) * 64 + 4 * h);
; #pragma unroll
;             for (int dt = 0; dt < 2; ++dt)
; #pragma unroll
;                 for (int g = 0; g < 4; ++g) {
;                     const int d0 = (dt << 9) | (g << 7);
;                     const u32x2 gv = *(const u32x2*)(grow + d0);
;                     u32x2 o; o.x = pk2(silu_mul(acc[u][dt][4 * g] * inv, bf_lo(gv.x)), silu_mul(acc[u][dt][4 * g + 1] * inv, bf_hi(gv.x)));
;                     o.y = pk2(silu_mul(acc[u][dt][4 * g + 2] * inv, bf_lo(gv.y)), silu_mul(acc[u][dt][4 * g + 3] * inv, bf_hi(gv.y)));
;                     *(u32x2*)(orow + d0) = o;
;                 }
;         }
;     }
	v_lshlrev_b32_e32 v210, 16, v178
	v_and_b32_e32 v211, 0xffff0000, v178
	v_lshlrev_b32_e32 v212, 16, v179
	v_and_b32_e32 v213, 0xffff0000, v179
	v_mul_f32_e32 v214, 0xbfb8aa3b, v210
	v_mul_f32_e32 v215, 0xbfb8aa3b, v211
	v_mul_f32_e32 v216, 0xbfb8aa3b, v212
	v_mul_f32_e32 v217, 0xbfb8aa3b, v213
	v_exp_f32_e32 v214, v214
	v_exp_f32_e32 v215, v215
	v_exp_f32_e32 v216, v216
	v_exp_f32_e32 v217, v217
	v_pk_mul_f32 v[50:51], v[50:51], v[210:211]
	v_pk_mul_f32 v[52:53], v[52:53], v[212:213]
	v_add_f32_e32 v214, 1.0, v214
	v_add_f32_e32 v215, 1.0, v215
	v_add_f32_e32 v216, 1.0, v216
	v_add_f32_e32 v217, 1.0, v217
	v_rcp_f32_e32 v214, v214
	v_rcp_f32_e32 v215, v215
	v_rcp_f32_e32 v216, v216
	v_rcp_f32_e32 v217, v217
	v_pk_mul_f32 v[50:51], v[50:51], v[214:215]
	v_pk_mul_f32 v[52:53], v[52:53], v[216:217]
	v_cvt_pk_bf16_f32 v50, v50, v51
	v_cvt_pk_bf16_f32 v51, v52, v53
	s_waitcnt vmcnt(15)
	v_lshlrev_b32_e32 v218, 16, v180
	v_and_b32_e32 v219, 0xffff0000, v180
	v_lshlrev_b32_e32 v220, 16, v181
	v_and_b32_e32 v221, 0xffff0000, v181
	v_mul_f32_e32 v222, 0xbfb8aa3b, v218
	v_mul_f32_e32 v223, 0xbfb8aa3b, v219
	v_mul_f32_e32 v224, 0xbfb8aa3b, v220
	v_mul_f32_e32 v225, 0xbfb8aa3b, v221
	v_exp_f32_e32 v222, v222
	v_exp_f32_e32 v223, v223
	v_exp_f32_e32 v224, v224
	v_exp_f32_e32 v225, v225
	v_pk_mul_f32 v[54:55], v[54:55], v[218:219]
	v_pk_mul_f32 v[56:57], v[56:57], v[220:221]
	v_add_f32_e32 v222, 1.0, v222
	v_add_f32_e32 v223, 1.0, v223
	v_add_f32_e32 v224, 1.0, v224
	v_add_f32_e32 v225, 1.0, v225
	v_rcp_f32_e32 v222, v222
	v_rcp_f32_e32 v223, v223
	v_rcp_f32_e32 v224, v224
	v_rcp_f32_e32 v225, v225
	v_pk_mul_f32 v[54:55], v[54:55], v[222:223]
	v_pk_mul_f32 v[56:57], v[56:57], v[224:225]
	v_cvt_pk_bf16_f32 v54, v54, v55
	v_cvt_pk_bf16_f32 v55, v56, v57
	s_waitcnt vmcnt(14)
	v_lshlrev_b32_e32 v210, 16, v182
	v_and_b32_e32 v211, 0xffff0000, v182
	v_lshlrev_b32_e32 v212, 16, v183
	v_and_b32_e32 v213, 0xffff0000, v183
	v_mul_f32_e32 v214, 0xbfb8aa3b, v210
	v_mul_f32_e32 v215, 0xbfb8aa3b, v211
	v_mul_f32_e32 v216, 0xbfb8aa3b, v212
	v_mul_f32_e32 v217, 0xbfb8aa3b, v213
	v_exp_f32_e32 v214, v214
	v_exp_f32_e32 v215, v215
	v_exp_f32_e32 v216, v216
	v_exp_f32_e32 v217, v217
	v_pk_mul_f32 v[58:59], v[58:59], v[210:211]
	v_pk_mul_f32 v[60:61], v[60:61], v[212:213]
	v_add_f32_e32 v214, 1.0, v214
	v_add_f32_e32 v215, 1.0, v215
	v_add_f32_e32 v216, 1.0, v216
	v_add_f32_e32 v217, 1.0, v217
	v_rcp_f32_e32 v214, v214
	v_rcp_f32_e32 v215, v215
	v_rcp_f32_e32 v216, v216
	v_rcp_f32_e32 v217, v217
	v_pk_mul_f32 v[58:59], v[58:59], v[214:215]
	v_pk_mul_f32 v[60:61], v[60:61], v[216:217]
	v_cvt_pk_bf16_f32 v58, v58, v59
	v_cvt_pk_bf16_f32 v59, v60, v61
	s_waitcnt vmcnt(13)
	v_lshlrev_b32_e32 v218, 16, v184
	v_and_b32_e32 v219, 0xffff0000, v184
	v_lshlrev_b32_e32 v220, 16, v185
	v_and_b32_e32 v221, 0xffff0000, v185
	v_mul_f32_e32 v222, 0xbfb8aa3b, v218
	v_mul_f32_e32 v223, 0xbfb8aa3b, v219
	v_mul_f32_e32 v224, 0xbfb8aa3b, v220
	v_mul_f32_e32 v225, 0xbfb8aa3b, v221
	v_exp_f32_e32 v222, v222
	v_exp_f32_e32 v223, v223
	v_exp_f32_e32 v224, v224
	v_exp_f32_e32 v225, v225
	v_pk_mul_f32 v[62:63], v[62:63], v[218:219]
	v_pk_mul_f32 v[64:65], v[64:65], v[220:221]
	v_add_f32_e32 v222, 1.0, v222
	v_add_f32_e32 v223, 1.0, v223
	v_add_f32_e32 v224, 1.0, v224
	v_add_f32_e32 v225, 1.0, v225
	v_rcp_f32_e32 v222, v222
	v_rcp_f32_e32 v223, v223
	v_rcp_f32_e32 v224, v224
	v_rcp_f32_e32 v225, v225
	v_pk_mul_f32 v[62:63], v[62:63], v[222:223]
	v_pk_mul_f32 v[64:65], v[64:65], v[224:225]
	v_cvt_pk_bf16_f32 v62, v62, v63
	v_cvt_pk_bf16_f32 v63, v64, v65
	s_waitcnt vmcnt(12)
	v_lshlrev_b32_e32 v210, 16, v186
	v_and_b32_e32 v211, 0xffff0000, v186
	v_lshlrev_b32_e32 v212, 16, v187
	v_and_b32_e32 v213, 0xffff0000, v187
	v_mul_f32_e32 v214, 0xbfb8aa3b, v210
	v_mul_f32_e32 v215, 0xbfb8aa3b, v211
	v_mul_f32_e32 v216, 0xbfb8aa3b, v212
	v_mul_f32_e32 v217, 0xbfb8aa3b, v213
	v_exp_f32_e32 v214, v214
	v_exp_f32_e32 v215, v215
	v_exp_f32_e32 v216, v216
	v_exp_f32_e32 v217, v217
	v_pk_mul_f32 v[34:35], v[34:35], v[210:211]
	v_pk_mul_f32 v[36:37], v[36:37], v[212:213]
	v_add_f32_e32 v214, 1.0, v214
	v_add_f32_e32 v215, 1.0, v215
	v_add_f32_e32 v216, 1.0, v216
	v_add_f32_e32 v217, 1.0, v217
	v_rcp_f32_e32 v214, v214
	v_rcp_f32_e32 v215, v215
	v_rcp_f32_e32 v216, v216
	v_rcp_f32_e32 v217, v217
	v_pk_mul_f32 v[34:35], v[34:35], v[214:215]
	v_pk_mul_f32 v[36:37], v[36:37], v[216:217]
	v_cvt_pk_bf16_f32 v34, v34, v35
	v_cvt_pk_bf16_f32 v35, v36, v37
	s_waitcnt vmcnt(11)
	v_lshlrev_b32_e32 v218, 16, v188
	v_and_b32_e32 v219, 0xffff0000, v188
	v_lshlrev_b32_e32 v220, 16, v189
	v_and_b32_e32 v221, 0xffff0000, v189
	v_mul_f32_e32 v222, 0xbfb8aa3b, v218
	v_mul_f32_e32 v223, 0xbfb8aa3b, v219
	v_mul_f32_e32 v224, 0xbfb8aa3b, v220
	v_mul_f32_e32 v225, 0xbfb8aa3b, v221
	v_exp_f32_e32 v222, v222
	v_exp_f32_e32 v223, v223
	v_exp_f32_e32 v224, v224
	v_exp_f32_e32 v225, v225
	v_pk_mul_f32 v[38:39], v[38:39], v[218:219]
	v_pk_mul_f32 v[40:41], v[40:41], v[220:221]
	v_add_f32_e32 v222, 1.0, v222
	v_add_f32_e32 v223, 1.0, v223
	v_add_f32_e32 v224, 1.0, v224
	v_add_f32_e32 v225, 1.0, v225
	v_rcp_f32_e32 v222, v222
	v_rcp_f32_e32 v223, v223
	v_rcp_f32_e32 v224, v224
	v_rcp_f32_e32 v225, v225
	v_pk_mul_f32 v[38:39], v[38:39], v[222:223]
	v_pk_mul_f32 v[40:41], v[40:41], v[224:225]
	v_cvt_pk_bf16_f32 v38, v38, v39
	v_cvt_pk_bf16_f32 v39, v40, v41
	s_waitcnt vmcnt(10)
; DI unsigned pk2(float a, float b) { f32x2 v = {a, b}; bf16v2 r = __builtin_convertvector(v, bf16v2); return __builtin_bit_cast(unsigned, r); }
; DI float bf_lo(unsigned u) { return __uint_as_float(u << 16); }
; DI float bf_hi(unsigned u) { return __uint_as_float(u & 0xffff0000u); }
; DI size_t zrowU(int row0, int NT) { return ((size_t)((row0 >> 8) * NT) << 16) + (size_t)((((row0 >> 7) & 1) << 15) | (((row0 >> 5) & 1) << 14) | (((row0 >> 6) & 1) << 11)); }
; DI unsigned zlaneRC(int r5, int col) { return (unsigned)(((col >> 8) << 16) | ((r5 >> 4) << 13) | (((col >> 7) & 1) << 12) | (((col >> 5) & 3) << 9) | (((col >> 3) & 3) << 7) | ((r5 & 15) << 3) | (col & 7)); }
; DI float silu_mul(float o, float g) { return o * g * __builtin_amdgcn_rcpf(1.0f + __builtin_amdgcn_exp2f(g * -1.4426950408889634f)); }
; DI void attnA_item(bf16_t* z, const float* sinks, int hp, int qs, LAS bf16_t* vs, const LAS float* btab, int lane) {
;     ...
;     if (!metaq || c < NMETA) {
; #pragma unroll
;         for (int u = 0; u < 2; ++u) {
;             const float inv = 1.0f / l[u];
;             bf16_t* orow = z + zrowU(qrow0, 18) + zlaneRC(c, (2 * hp + u) * 64 + 4 * h);
;             const bf16_t* grow = z + zrowU(qrow0, 18) + zlaneRC(c, 2560 + (2 * hp + u) * 64 + 4 * h);
; #pragma unroll
;             for (int dt = 0; dt < 2; ++dt)
; #pragma unroll
;                 for (int g = 0; g < 4; ++g) {
;                     const int d0 = (dt << 9) | (g << 7);
;                     const u32x2 gv = *(const u32x2*)(grow + d0);
;                     u32x2 o; o.x = pk2(silu_mul(acc[u][dt][4 * g] * inv, bf_lo(gv.x)), silu_mul(acc[u][dt][4 * g + 1] * inv, bf_hi(gv.x)));
;                     o.y = pk2(silu_mul(acc[u][dt][4 * g + 2] * inv, bf_lo(gv.y)), silu_mul(acc[u][dt][4 * g + 3] * inv, bf_hi(gv.y)));
;                     *(u32x2*)(orow + d0) = o;
;                 }
;         }
;     }
	v_lshlrev_b32_e32 v210, 16, v190
	v_and_b32_e32 v211, 0xffff0000, v190
	v_lshlrev_b32_e32 v212, 16, v191
	v_and_b32_e32 v213, 0xffff0000, v191
	v_mul_f32_e32 v214, 0xbfb8aa3b, v210
	v_mul_f32_e32 v215, 0xbfb8aa3b, v211
	v_mul_f32_e32 v216, 0xbfb8aa3b, v212
	v_mul_f32_e32 v217, 0xbfb8aa3b, v213
	v_exp_f32_e32 v214, v214
	v_exp_f32_e32 v215, v215
	v_exp_f32_e32 v216, v216
	v_exp_f32_e32 v217, v217
	v_pk_mul_f32 v[42:43], v[42:43], v[210:211]
	v_pk_mul_f32 v[44:45], v[44:45], v[212:213]
	v_add_f32_e32 v214, 1.0, v214
	v_add_f32_e32 v215, 1.0, v215
	v_add_f32_e32 v216, 1.0, v216
	v_add_f32_e32 v217, 1.0, v217
	v_rcp_f32_e32 v214, v214
	v_rcp_f32_e32 v215, v215
	v_rcp_f32_e32 v216, v216
	v_rcp_f32_e32 v217, v217
	v_pk_mul_f32 v[42:43], v[42:43], v[214:215]
	v_pk_mul_f32 v[44:45], v[44:45], v[216:217]
	v_cvt_pk_bf16_f32 v42, v42, v43
	v_cvt_pk_bf16_f32 v43, v44, v45
	s_waitcnt vmcnt(9)
	v_lshlrev_b32_e32 v218, 16, v192
	v_and_b32_e32 v219, 0xffff0000, v192
	v_lshlrev_b32_e32 v220, 16, v193
	v_and_b32_e32 v221, 0xffff0000, v193
	v_mul_f32_e32 v222, 0xbfb8aa3b, v218
	v_mul_f32_e32 v223, 0xbfb8aa3b, v219
	v_mul_f32_e32 v224, 0xbfb8aa3b, v220
	v_mul_f32_e32 v225, 0xbfb8aa3b, v221
	v_exp_f32_e32 v222, v222
	v_exp_f32_e32 v223, v223
	v_exp_f32_e32 v224, v224
	v_exp_f32_e32 v225, v225
	v_pk_mul_f32 v[46:47], v[46:47], v[218:219]
	v_pk_mul_f32 v[48:49], v[48:49], v[220:221]
	v_add_f32_e32 v222, 1.0, v222
	v_add_f32_e32 v223, 1.0, v223
	v_add_f32_e32 v224, 1.0, v224
	v_add_f32_e32 v225, 1.0, v225
	v_rcp_f32_e32 v222, v222
	v_rcp_f32_e32 v223, v223
	v_rcp_f32_e32 v224, v224
	v_rcp_f32_e32 v225, v225
	v_pk_mul_f32 v[46:47], v[46:47], v[222:223]
	v_pk_mul_f32 v[48:49], v[48:49], v[224:225]
	v_cvt_pk_bf16_f32 v46, v46, v47
	v_cvt_pk_bf16_f32 v47, v48, v49
	s_waitcnt vmcnt(8)
	v_lshlrev_b32_e32 v210, 16, v194
	v_and_b32_e32 v211, 0xffff0000, v194
	v_lshlrev_b32_e32 v212, 16, v195
	v_and_b32_e32 v213, 0xffff0000, v195
	v_mul_f32_e32 v214, 0xbfb8aa3b, v210
	v_mul_f32_e32 v215, 0xbfb8aa3b, v211
	v_mul_f32_e32 v216, 0xbfb8aa3b, v212
	v_mul_f32_e32 v217, 0xbfb8aa3b, v213
	v_exp_f32_e32 v214, v214
	v_exp_f32_e32 v215, v215
	v_exp_f32_e32 v216, v216
	v_exp_f32_e32 v217, v217
	v_pk_mul_f32 v[18:19], v[18:19], v[210:211]
	v_pk_mul_f32 v[20:21], v[20:21], v[212:213]
	v_add_f32_e32 v214, 1.0, v214
	v_add_f32_e32 v215, 1.0, v215
	v_add_f32_e32 v216, 1.0, v216
	v_add_f32_e32 v217, 1.0, v217
	v_rcp_f32_e32 v214, v214
	v_rcp_f32_e32 v215, v215
	v_rcp_f32_e32 v216, v216
	v_rcp_f32_e32 v217, v217
	v_pk_mul_f32 v[18:19], v[18:19], v[214:215]
	v_pk_mul_f32 v[20:21], v[20:21], v[216:217]
	v_cvt_pk_bf16_f32 v18, v18, v19
	v_cvt_pk_bf16_f32 v19, v20, v21
	s_waitcnt vmcnt(7)
	v_lshlrev_b32_e32 v218, 16, v196
	v_and_b32_e32 v219, 0xffff0000, v196
	v_lshlrev_b32_e32 v220, 16, v197
	v_and_b32_e32 v221, 0xffff0000, v197
	v_mul_f32_e32 v222, 0xbfb8aa3b, v218
	v_mul_f32_e32 v223, 0xbfb8aa3b, v219
	v_mul_f32_e32 v224, 0xbfb8aa3b, v220
	v_mul_f32_e32 v225, 0xbfb8aa3b, v221
	v_exp_f32_e32 v222, v222
	v_exp_f32_e32 v223, v223
	v_exp_f32_e32 v224, v224
	v_exp_f32_e32 v225, v225
	v_pk_mul_f32 v[22:23], v[22:23], v[218:219]
	v_pk_mul_f32 v[24:25], v[24:25], v[220:221]
	v_add_f32_e32 v222, 1.0, v222
	v_add_f32_e32 v223, 1.0, v223
	v_add_f32_e32 v224, 1.0, v224
	v_add_f32_e32 v225, 1.0, v225
	v_rcp_f32_e32 v222, v222
	v_rcp_f32_e32 v223, v223
	v_rcp_f32_e32 v224, v224
	v_rcp_f32_e32 v225, v225
	v_pk_mul_f32 v[22:23], v[22:23], v[222:223]
	v_pk_mul_f32 v[24:25], v[24:25], v[224:225]
	v_cvt_pk_bf16_f32 v22, v22, v23
	v_cvt_pk_bf16_f32 v23, v24, v25
	s_waitcnt vmcnt(6)
	v_lshlrev_b32_e32 v210, 16, v198
	v_and_b32_e32 v211, 0xffff0000, v198
	v_lshlrev_b32_e32 v212, 16, v199
	v_and_b32_e32 v213, 0xffff0000, v199
	v_mul_f32_e32 v214, 0xbfb8aa3b, v210
	v_mul_f32_e32 v215, 0xbfb8aa3b, v211
	v_mul_f32_e32 v216, 0xbfb8aa3b, v212
	v_mul_f32_e32 v217, 0xbfb8aa3b, v213
	v_exp_f32_e32 v214, v214
	v_exp_f32_e32 v215, v215
	v_exp_f32_e32 v216, v216
	v_exp_f32_e32 v217, v217
	v_pk_mul_f32 v[26:27], v[26:27], v[210:211]
	v_pk_mul_f32 v[28:29], v[28:29], v[212:213]
	v_add_f32_e32 v214, 1.0, v214
	v_add_f32_e32 v215, 1.0, v215
	v_add_f32_e32 v216, 1.0, v216
	v_add_f32_e32 v217, 1.0, v217
	v_rcp_f32_e32 v214, v214
	v_rcp_f32_e32 v215, v215
	v_rcp_f32_e32 v216, v216
	v_rcp_f32_e32 v217, v217
	v_pk_mul_f32 v[26:27], v[26:27], v[214:215]
	v_pk_mul_f32 v[28:29], v[28:29], v[216:217]
	v_cvt_pk_bf16_f32 v26, v26, v27
	v_cvt_pk_bf16_f32 v27, v28, v29
	s_waitcnt vmcnt(5)
; DI unsigned pk2(float a, float b) { f32x2 v = {a, b}; bf16v2 r = __builtin_convertvector(v, bf16v2); return __builtin_bit_cast(unsigned, r); }
; DI float bf_lo(unsigned u) { return __uint_as_float(u << 16); }
; DI float bf_hi(unsigned u) { return __uint_as_float(u & 0xffff0000u); }
; DI size_t zrowU(int row0, int NT) { return ((size_t)((row0 >> 8) * NT) << 16) + (size_t)((((row0 >> 7) & 1) << 15) | (((row0 >> 5) & 1) << 14) | (((row0 >> 6) & 1) << 11)); }
; DI unsigned zlaneRC(int r5, int col) { return (unsigned)(((col >> 8) << 16) | ((r5 >> 4) << 13) | (((col >> 7) & 1) << 12) | (((col >> 5) & 3) << 9) | (((col >> 3) & 3) << 7) | ((r5 & 15) << 3) | (col & 7)); }
; DI float silu_mul(float o, float g) { return o * g * __builtin_amdgcn_rcpf(1.0f + __builtin_amdgcn_exp2f(g * -1.4426950408889634f)); }
; DI void attnA_item(bf16_t* z, const float* sinks, int hp, int qs, LAS bf16_t* vs, const LAS float* btab, int lane) {
;     ...
;     if (!metaq || c < NMETA) {
; #pragma unroll
;         for (int u = 0; u < 2; ++u) {
;             const float inv = 1.0f / l[u];
;             bf16_t* orow = z + zrowU(qrow0, 18) + zlaneRC(c, (2 * hp + u) * 64 + 4 * h);
;             const bf16_t* grow = z + zrowU(qrow0, 18) + zlaneRC(c, 2560 + (2 * hp + u) * 64 + 4 * h);
; #pragma unroll
;             for (int dt = 0; dt < 2; ++dt)
; #pragma unroll
;                 for (int g = 0; g < 4; ++g) {
;                     const int d0 = (dt << 9) | (g << 7);
;                     const u32x2 gv = *(const u32x2*)(grow + d0);
;                     u32x2 o; o.x = pk2(silu_mul(acc[u][dt][4 * g] * inv, bf_lo(gv.x)), silu_mul(acc[u][dt][4 * g + 1] * inv, bf_hi(gv.x)));
;                     o.y = pk2(silu_mul(acc[u][dt][4 * g + 2] * inv, bf_lo(gv.y)), silu_mul(acc[u][dt][4 * g + 3] * inv, bf_hi(gv.y)));
;                     *(u32x2*)(orow + d0) = o;
;                 }
;         }
;     }
	v_lshlrev_b32_e32 v218, 16, v200
	v_and_b32_e32 v219, 0xffff0000, v200
	v_lshlrev_b32_e32 v220, 16, v201
	v_and_b32_e32 v221, 0xffff0000, v201
	v_mul_f32_e32 v222, 0xbfb8aa3b, v218
	v_mul_f32_e32 v223, 0xbfb8aa3b, v219
	v_mul_f32_e32 v224, 0xbfb8aa3b, v220
	v_mul_f32_e32 v225, 0xbfb8aa3b, v221
	v_exp_f32_e32 v222, v222
	v_exp_f32_e32 v223, v223
	v_exp_f32_e32 v224, v224
	v_exp_f32_e32 v225, v225
	v_pk_mul_f32 v[30:31], v[30:31], v[218:219]
	v_pk_mul_f32 v[32:33], v[32:33], v[220:221]
	v_add_f32_e32 v222, 1.0, v222
	v_add_f32_e32 v223, 1.0, v223
	v_add_f32_e32 v224, 1.0, v224
	v_add_f32_e32 v225, 1.0, v225
	v_rcp_f32_e32 v222, v222
	v_rcp_f32_e32 v223, v223
	v_rcp_f32_e32 v224, v224
	v_rcp_f32_e32 v225, v225
	v_pk_mul_f32 v[30:31], v[30:31], v[222:223]
	v_pk_mul_f32 v[32:33], v[32:33], v[224:225]
	v_cvt_pk_bf16_f32 v30, v30, v31
	v_cvt_pk_bf16_f32 v31, v32, v33
	s_waitcnt vmcnt(4)
	v_lshlrev_b32_e32 v210, 16, v202
	v_and_b32_e32 v211, 0xffff0000, v202
	v_lshlrev_b32_e32 v212, 16, v203
	v_and_b32_e32 v213, 0xffff0000, v203
	v_mul_f32_e32 v214, 0xbfb8aa3b, v210
	v_mul_f32_e32 v215, 0xbfb8aa3b, v211
	v_mul_f32_e32 v216, 0xbfb8aa3b, v212
	v_mul_f32_e32 v217, 0xbfb8aa3b, v213
	v_exp_f32_e32 v214, v214
	v_exp_f32_e32 v215, v215
	v_exp_f32_e32 v216, v216
	v_exp_f32_e32 v217, v217
	v_pk_mul_f32 v[2:3], v[2:3], v[210:211]
	v_pk_mul_f32 v[4:5], v[4:5], v[212:213]
	v_add_f32_e32 v214, 1.0, v214
	v_add_f32_e32 v215, 1.0, v215
	v_add_f32_e32 v216, 1.0, v216
	v_add_f32_e32 v217, 1.0, v217
	v_rcp_f32_e32 v214, v214
	v_rcp_f32_e32 v215, v215
	v_rcp_f32_e32 v216, v216
	v_rcp_f32_e32 v217, v217
	v_pk_mul_f32 v[2:3], v[2:3], v[214:215]
	v_pk_mul_f32 v[4:5], v[4:5], v[216:217]
	v_cvt_pk_bf16_f32 v2, v2, v3
	v_cvt_pk_bf16_f32 v3, v4, v5
	s_waitcnt vmcnt(3)
	v_lshlrev_b32_e32 v218, 16, v204
	v_and_b32_e32 v219, 0xffff0000, v204
	v_lshlrev_b32_e32 v220, 16, v205
	v_and_b32_e32 v221, 0xffff0000, v205
	v_mul_f32_e32 v222, 0xbfb8aa3b, v218
	v_mul_f32_e32 v223, 0xbfb8aa3b, v219
	v_mul_f32_e32 v224, 0xbfb8aa3b, v220
	v_mul_f32_e32 v225, 0xbfb8aa3b, v221
	v_exp_f32_e32 v222, v222
	v_exp_f32_e32 v223, v223
	v_exp_f32_e32 v224, v224
	v_exp_f32_e32 v225, v225
	v_pk_mul_f32 v[6:7], v[6:7], v[218:219]
	v_pk_mul_f32 v[8:9], v[8:9], v[220:221]
	v_add_f32_e32 v222, 1.0, v222
	v_add_f32_e32 v223, 1.0, v223
	v_add_f32_e32 v224, 1.0, v224
	v_add_f32_e32 v225, 1.0, v225
	v_rcp_f32_e32 v222, v222
	v_rcp_f32_e32 v223, v223
	v_rcp_f32_e32 v224, v224
	v_rcp_f32_e32 v225, v225
	v_pk_mul_f32 v[6:7], v[6:7], v[222:223]
	v_pk_mul_f32 v[8:9], v[8:9], v[224:225]
	v_cvt_pk_bf16_f32 v6, v6, v7
	v_cvt_pk_bf16_f32 v7, v8, v9
	s_waitcnt vmcnt(2)
	v_lshlrev_b32_e32 v210, 16, v206
	v_and_b32_e32 v211, 0xffff0000, v206
	v_lshlrev_b32_e32 v212, 16, v207
	v_and_b32_e32 v213, 0xffff0000, v207
	v_mul_f32_e32 v214, 0xbfb8aa3b, v210
	v_mul_f32_e32 v215, 0xbfb8aa3b, v211
	v_mul_f32_e32 v216, 0xbfb8aa3b, v212
	v_mul_f32_e32 v217, 0xbfb8aa3b, v213
	v_exp_f32_e32 v214, v214
	v_exp_f32_e32 v215, v215
	v_exp_f32_e32 v216, v216
	v_exp_f32_e32 v217, v217
	v_pk_mul_f32 v[10:11], v[10:11], v[210:211]
	v_pk_mul_f32 v[12:13], v[12:13], v[212:213]
	v_add_f32_e32 v214, 1.0, v214
	v_add_f32_e32 v215, 1.0, v215
	v_add_f32_e32 v216, 1.0, v216
	v_add_f32_e32 v217, 1.0, v217
	v_rcp_f32_e32 v214, v214
	v_rcp_f32_e32 v215, v215
	v_rcp_f32_e32 v216, v216
	v_rcp_f32_e32 v217, v217
	v_pk_mul_f32 v[10:11], v[10:11], v[214:215]
	v_pk_mul_f32 v[12:13], v[12:13], v[216:217]
	v_cvt_pk_bf16_f32 v10, v10, v11
	v_cvt_pk_bf16_f32 v11, v12, v13
	s_waitcnt vmcnt(1)
	v_lshlrev_b32_e32 v218, 16, v208
	v_and_b32_e32 v219, 0xffff0000, v208
	v_lshlrev_b32_e32 v220, 16, v209
	v_and_b32_e32 v221, 0xffff0000, v209
	v_mul_f32_e32 v222, 0xbfb8aa3b, v218
	v_mul_f32_e32 v223, 0xbfb8aa3b, v219
	v_mul_f32_e32 v224, 0xbfb8aa3b, v220
	v_mul_f32_e32 v225, 0xbfb8aa3b, v221
	v_exp_f32_e32 v222, v222
	v_exp_f32_e32 v223, v223
	v_exp_f32_e32 v224, v224
	v_exp_f32_e32 v225, v225
	v_pk_mul_f32 v[14:15], v[14:15], v[218:219]
	v_pk_mul_f32 v[16:17], v[16:17], v[220:221]
	v_add_f32_e32 v222, 1.0, v222
	v_add_f32_e32 v223, 1.0, v223
	v_add_f32_e32 v224, 1.0, v224
	v_add_f32_e32 v225, 1.0, v225
	v_rcp_f32_e32 v222, v222
	v_rcp_f32_e32 v223, v223
	v_rcp_f32_e32 v224, v224
	v_rcp_f32_e32 v225, v225
	v_pk_mul_f32 v[14:15], v[14:15], v[222:223]
	v_pk_mul_f32 v[16:17], v[16:17], v[224:225]
	v_cvt_pk_bf16_f32 v14, v14, v15
	v_cvt_pk_bf16_f32 v15, v16, v17
	global_store_dwordx2 v[138:139], v[50:51], off
	global_store_dwordx2 v[138:139], v[54:55], off offset:256
	global_store_dwordx2 v[138:139], v[58:59], off offset:512
	global_store_dwordx2 v[138:139], v[62:63], off offset:768
	global_store_dwordx2 v[138:139], v[34:35], off offset:1024
	global_store_dwordx2 v[138:139], v[38:39], off offset:1280
	global_store_dwordx2 v[138:139], v[42:43], off offset:1536
	global_store_dwordx2 v[138:139], v[46:47], off offset:1792
	global_store_dwordx2 v[142:143], v[18:19], off
	global_store_dwordx2 v[142:143], v[22:23], off offset:256
	global_store_dwordx2 v[142:143], v[26:27], off offset:512
	global_store_dwordx2 v[142:143], v[30:31], off offset:768
	global_store_dwordx2 v[142:143], v[2:3], off offset:1024
	global_store_dwordx2 v[142:143], v[6:7], off offset:1280
	global_store_dwordx2 v[142:143], v[10:11], off offset:1536
	global_store_dwordx2 v[142:143], v[14:15], off offset:1792
	s_branch .LBB0_177

; __global__ void __launch_bounds__(NTHREADS) hybrid_fwd(Params p) {
	.amdhsa_kernel _Z10hybrid_fwd6Params
		.amdhsa_group_segment_fixed_size 0
		.amdhsa_private_segment_fixed_size 0
		.amdhsa_kernarg_size 360
		.amdhsa_user_sgpr_count 2
		.amdhsa_user_sgpr_dispatch_ptr 0
		.amdhsa_user_sgpr_queue_ptr 0
		.amdhsa_user_sgpr_kernarg_segment_ptr 1
		.amdhsa_user_sgpr_dispatch_id 0
		.amdhsa_user_sgpr_kernarg_preload_length 0
		.amdhsa_user_sgpr_kernarg_preload_offset 0
		.amdhsa_user_sgpr_private_segment_size 0
		.amdhsa_uses_dynamic_stack 0
		.amdhsa_enable_private_segment 0
		.amdhsa_system_sgpr_workgroup_id_x 1
		.amdhsa_system_sgpr_workgroup_id_y 0
		.amdhsa_system_sgpr_workgroup_id_z 0
		.amdhsa_system_sgpr_workgroup_info 0
		.amdhsa_system_vgpr_workitem_id 2
		.amdhsa_next_free_vgpr 248
		.amdhsa_next_free_sgpr 102
		.amdhsa_accum_offset 248
		.amdhsa_reserve_vcc 1
		.amdhsa_float_round_mode_32 0
		.amdhsa_float_round_mode_16_64 0
		.amdhsa_float_denorm_mode_32 3
		.amdhsa_float_denorm_mode_16_64 3
		.amdhsa_dx10_clamp 1
		.amdhsa_ieee_mode 1
		.amdhsa_fp16_overflow 0
		.amdhsa_tg_split 0
		.amdhsa_exception_fp_ieee_invalid_op 0
		.amdhsa_exception_fp_denorm_src 0
		.amdhsa_exception_fp_ieee_div_zero 0
		.amdhsa_exception_fp_ieee_overflow 0
		.amdhsa_exception_fp_ieee_underflow 0
		.amdhsa_exception_fp_ieee_inexact 0
		.amdhsa_exception_int_div_zero 0
	.end_amdhsa_kernel

; __global__ void __launch_bounds__(NTHREADS) hybrid_fwd(Params p) {
amdhsa.kernels:
  - .agpr_count:     0
    .args:
      - .offset:         0
        .size:           104
        .value_kind:     by_value
      - .offset:         104
        .size:           4
        .value_kind:     hidden_block_count_x
      - .offset:         108
        .size:           4
        .value_kind:     hidden_block_count_y
      - .offset:         112
        .size:           4
        .value_kind:     hidden_block_count_z
      - .offset:         116
        .size:           2
        .value_kind:     hidden_group_size_x
      - .offset:         118
        .size:           2
        .value_kind:     hidden_group_size_y
      - .offset:         120
        .size:           2
        .value_kind:     hidden_group_size_z
      - .offset:         122
        .size:           2
        .value_kind:     hidden_remainder_x
      - .offset:         124
        .size:           2
        .value_kind:     hidden_remainder_y
      - .offset:         126
        .size:           2
        .value_kind:     hidden_remainder_z
      - .offset:         144
        .size:           8
        .value_kind:     hidden_global_offset_x
      - .offset:         152
        .size:           8
        .value_kind:     hidden_global_offset_y
      - .offset:         160
        .size:           8
        .value_kind:     hidden_global_offset_z
      - .offset:         168
        .size:           2
        .value_kind:     hidden_grid_dims
      - .offset:         192
        .size:           8
        .value_kind:     hidden_multigrid_sync_arg
      - .offset:         224
        .size:           4
        .value_kind:     hidden_dynamic_lds_size
    .group_segment_fixed_size: 0
    .kernarg_segment_align: 8
    .kernarg_segment_size: 360
    .language:       OpenCL C
    .language_version:
      - 2
      - 0
    .max_flat_workgroup_size: 512
    .name:           _Z10hybrid_fwd6Params
    .private_segment_fixed_size: 0
    .sgpr_count:     108
    .sgpr_spill_count: 95
    .symbol:         _Z10hybrid_fwd6Params.kd
    .uniform_work_group_size: 1
    .uses_dynamic_stack: false
    .vgpr_count:     248
    .vgpr_spill_count: 0
    .wavefront_size: 64
